# v038 + dead latch v_xor (K write-address regs) removed and conservative s_nop 3 after readlane trimmed in the prompt MLA loop
# baseline (speedup 1.0000x reference)
.LBB0_555:
	s_or_b64 exec, exec, s[22:23]
	s_xor_b32 s98, s98, 0x10000
	v_xor_b32_e32 v188, 0x10000, v188
	v_xor_b32_e32 v192, 0x10000, v192
	v_xor_b32_e32 v193, 0x10000, v193
	v_xor_b32_e32 v194, 0x10000, v194
	v_readlane_b32 s12, v253, 29
	v_readlane_b32 s13, v253, 30
	s_add_i32 s12, s12, 64
	s_add_i32 s58, s58, 1
	v_writelane_b32 v253, s12, 29
	s_cmp_eq_u32 s57, s58
	s_nop 0
	v_writelane_b32 v253, s13, 30
	s_cbranch_scc1 .LBB0_573
.LBB0_556:
	s_waitcnt vmcnt(0)
	ds_write2_b64 v192, v[168:169], v[170:171] offset1:1
	ds_write2_b64 v193, v[164:165], v[166:167] offset1:1
	s_cmp_ge_u32 s58, s27
	s_cbranch_scc1 .Lt_last
	v_readlane_b32 s12, v253, 29
	v_readlane_b32 s13, v253, 30
	s_nop 0
	s_lshl_b64 s[12:13], s[12:13], 1
	s_nop 0
	v_lshl_add_u64 v[158:159], v[172:173], 0, s[12:13]
	v_lshl_add_u64 v[160:161], v[174:175], 0, s[12:13]
	global_load_dwordx4 v[168:171], v[158:159], off
	global_load_dwordx4 v[164:167], v[160:161], off
	v_readfirstlane_b32 s12, v152
	v_readfirstlane_b32 s13, v153
	v_readlane_b32 s22, v253, 29
	s_nop 0
	s_mul_i32 s23, s22, 0x140
	s_add_u32 s12, s12, s23
	s_addc_u32 s13, s13, 0
	s_xor_b32 s23, s98, 0x10000
	s_add_i32 s23, s23, s99
	s_waitcnt lgkmcnt(0)
	s_barrier
	ds_read_b128 v[196:199], v188
	ds_read_b128 v[202:205], v188 offset:32
	ds_read_b128 v[206:209], v188 offset:64
	ds_read_b128 v[210:213], v188 offset:96
	ds_read_b128 v[220:223], v188 offset:128
	ds_read_b128 v[224:227], v188 offset:160
	ds_read_b128 v[2:5], v188 offset:192
	ds_read_b128 v[6:9], v188 offset:224
	s_mov_b32 m0, s23
	s_nop 0
	global_load_lds_dwordx4 v154, s[12:13]
	s_add_i32 m0, s23, 0x2000
	s_nop 0
	global_load_lds_dwordx4 v155, s[12:13]
	s_cmp_ge_u32 s99, 0x1400
	s_cbranch_scc1 .LBB0_566
	s_add_i32 m0, s23, 0x4000
	s_nop 0
	global_load_lds_dwordx4 v156, s[12:13]
	s_branch .LBB0_566
